# gMLP spatial-gating item epilogue: the 18 u/bias loads of each 16-row half issued before the first wait (was 16 serial load->wait->store round trips per item); on top of v36
# baseline (speedup 1.0000x reference)
; __device__ __forceinline__ f32x4 mfma16(bf16x8 a, bf16x8 b, f32x4 c) { return __builtin_amdgcn_mfma_f32_16x16x32_bf16(a, b, c, 0, 0, 0); }
;     ...
;     for (int kt = 0; kt < nk; ++kt) {
;         lds_sync();
; #pragma unroll
;         for (int i = 0; i < 4; ++i) *(u32x4*)(sW + (srow + i * 32) * GST + skc) = rw[i];
;         lds_sync();
;         const int k0 = (kt + 1 < nk ? kt + 1 : kt) << 6;
;         const int ka = FRAG ? (k0 >> 5) * 512 : k0;
; #pragma unroll
;         for (int i = 0; i < 4; ++i) rw[i] = *(const u32x4*)(wp + (size_t)(i * 32) * ldw + k0);
;         bf16x8 wa[4], wb[4];
; #pragma unroll
;         for (int j = 0; j < 4; ++j) wa[j] = lds16(wr + (j * 16) * GST);
; #pragma unroll
;         for (int j = 0; j < 4; ++j) wb[j] = lds16(wr + ((j + 4) * 16) * GST);
;         __builtin_amdgcn_sched_barrier(0);
;         __builtin_amdgcn_s_setprio(1);
; #pragma unroll
;         for (int j = 0; j < 4; ++j)
; #pragma unroll
;             for (int i = 0; i < MI; ++i) acc[i][j] = mfma16(wa[j], __builtin_bit_cast(bf16x8, ra[i][0]), acc[i][j]);
;         __builtin_amdgcn_sched_barrier(0);
; #pragma unroll
;         for (int j = 0; j < 4; ++j) wa[j] = lds16(wr + (j * 16) * GST + 32);
;         __builtin_amdgcn_sched_barrier(0);
; #pragma unroll
;         for (int j = 0; j < 4; ++j)
; #pragma unroll
;             for (int i = 0; i < MI; ++i) acc[i][j + 4] = mfma16(wb[j], __builtin_bit_cast(bf16x8, ra[i][0]), acc[i][j + 4]);
;         __builtin_amdgcn_sched_barrier(0);
; #pragma unroll
;         for (int i = 0; i < MI; ++i) ra[i][0] = *(const u32x4*)(ap + (size_t)i * ASI + ka);
; #pragma unroll
;         for (int j = 0; j < 4; ++j) wb[j] = lds16(wr + ((j + 4) * 16) * GST + 32);
;         __builtin_amdgcn_sched_barrier(0);
; #pragma unroll
;         for (int j = 0; j < 4; ++j)
; #pragma unroll
;             for (int i = 0; i < MI; ++i) acc[i][j] = mfma16(wa[j], __builtin_bit_cast(bf16x8, ra[i][1]), acc[i][j]);
;         __builtin_amdgcn_sched_barrier(0);
; #pragma unroll
;         for (int j = 0; j < 4; ++j)
; #pragma unroll
;             for (int i = 0; i < MI; ++i) acc[i][j + 4] = mfma16(wb[j], __builtin_bit_cast(bf16x8, ra[i][1]), acc[i][j + 4]);
;         __builtin_amdgcn_s_setprio(0);
;         __builtin_amdgcn_sched_barrier(0);
; #pragma unroll
;         for (int i = 0; i < MI; ++i) ra[i][1] = *(const u32x4*)(ap + (size_t)i * ASI + ka + ASK);
;     }
.LBB0_175:
	s_waitcnt vmcnt(63) expcnt(7) lgkmcnt(15)
	s_barrier
	s_waitcnt vmcnt(11)
	ds_write_b128 v131, v[112:115]
	s_waitcnt vmcnt(9)
	ds_write_b128 v131, v[124:127] offset:4608
	s_waitcnt vmcnt(7)
	ds_write_b128 v131, v[120:123] offset:9216
	s_waitcnt vmcnt(5)
	ds_write_b128 v131, v[116:119] offset:13824
	s_waitcnt lgkmcnt(0)
	s_barrier
	ds_read_b128 v[112:115], v130
	ds_read_b128 v[116:119], v130 offset:2304
	ds_read_b128 v[120:123], v130 offset:4608
	ds_read_b128 v[124:127], v130 offset:6912
	ds_read_b128 v[132:135], v130 offset:9216
	ds_read_b128 v[136:139], v130 offset:11520
	ds_read_b128 v[140:143], v130 offset:13824
	ds_read_b128 v[144:147], v130 offset:16128
	s_setprio 1
	s_waitcnt lgkmcnt(7)
	v_mfma_f32_16x16x32_bf16 v[92:95], v[112:115], v[104:107], v[92:95]
	v_mfma_f32_16x16x32_bf16 v[28:31], v[112:115], v[108:111], v[28:31]
	s_waitcnt lgkmcnt(6)
	v_mfma_f32_16x16x32_bf16 v[64:67], v[116:119], v[104:107], v[64:67]
	v_mfma_f32_16x16x32_bf16 v[24:27], v[116:119], v[108:111], v[24:27]
	s_waitcnt lgkmcnt(5)
	v_mfma_f32_16x16x32_bf16 v[52:55], v[120:123], v[104:107], v[52:55]
	v_mfma_f32_16x16x32_bf16 v[20:23], v[120:123], v[108:111], v[20:23]
	s_waitcnt lgkmcnt(4)
	v_mfma_f32_16x16x32_bf16 v[48:51], v[124:127], v[104:107], v[48:51]
	v_mfma_f32_16x16x32_bf16 v[16:19], v[124:127], v[108:111], v[16:19]
	ds_read_b128 v[112:115], v130 offset:64
	ds_read_b128 v[116:119], v130 offset:2368
	ds_read_b128 v[120:123], v130 offset:4672
	ds_read_b128 v[124:127], v130 offset:6976
	s_waitcnt lgkmcnt(7)
	v_mfma_f32_16x16x32_bf16 v[44:47], v[132:135], v[104:107], v[44:47]
	v_mfma_f32_16x16x32_bf16 v[12:15], v[132:135], v[108:111], v[12:15]
	s_waitcnt lgkmcnt(6)
	v_mfma_f32_16x16x32_bf16 v[40:43], v[136:139], v[104:107], v[40:43]
	v_mfma_f32_16x16x32_bf16 v[8:11], v[136:139], v[108:111], v[8:11]
	s_waitcnt lgkmcnt(5)
	v_mfma_f32_16x16x32_bf16 v[36:39], v[140:143], v[104:107], v[36:39]
	v_mfma_f32_16x16x32_bf16 v[4:7], v[140:143], v[108:111], v[4:7]
	s_waitcnt lgkmcnt(4)
	v_mfma_f32_16x16x32_bf16 v[32:35], v[144:147], v[104:107], v[32:35]
	v_mfma_f32_16x16x32_bf16 v[0:3], v[144:147], v[108:111], v[0:3]
	ds_read_b128 v[104:107], v130 offset:9280
	ds_read_b128 v[108:111], v130 offset:11584
	ds_read_b128 v[132:135], v130 offset:13888
	ds_read_b128 v[136:139], v130 offset:16192
	s_waitcnt lgkmcnt(7)
	v_mfma_f32_16x16x32_bf16 v[92:95], v[112:115], v[96:99], v[92:95]
	v_mfma_f32_16x16x32_bf16 v[28:31], v[112:115], v[100:103], v[28:31]
	s_waitcnt lgkmcnt(6)
	v_mfma_f32_16x16x32_bf16 v[64:67], v[116:119], v[96:99], v[64:67]
	v_mfma_f32_16x16x32_bf16 v[24:27], v[116:119], v[100:103], v[24:27]
	s_waitcnt lgkmcnt(5)
	v_mfma_f32_16x16x32_bf16 v[52:55], v[120:123], v[96:99], v[52:55]
	v_mfma_f32_16x16x32_bf16 v[20:23], v[120:123], v[100:103], v[20:23]
	s_waitcnt lgkmcnt(4)
	v_mfma_f32_16x16x32_bf16 v[48:51], v[124:127], v[96:99], v[48:51]
	v_mfma_f32_16x16x32_bf16 v[16:19], v[124:127], v[100:103], v[16:19]
	s_waitcnt lgkmcnt(3)
	v_mfma_f32_16x16x32_bf16 v[44:47], v[104:107], v[96:99], v[44:47]
	v_mfma_f32_16x16x32_bf16 v[12:15], v[104:107], v[100:103], v[12:15]
	s_waitcnt lgkmcnt(2)
	v_mfma_f32_16x16x32_bf16 v[40:43], v[108:111], v[96:99], v[40:43]
	v_mfma_f32_16x16x32_bf16 v[8:11], v[108:111], v[100:103], v[8:11]
	s_waitcnt lgkmcnt(1)
	v_mfma_f32_16x16x32_bf16 v[36:39], v[132:135], v[96:99], v[36:39]
	v_mfma_f32_16x16x32_bf16 v[4:7], v[132:135], v[100:103], v[4:7]
	s_waitcnt lgkmcnt(0)
	v_mfma_f32_16x16x32_bf16 v[32:35], v[136:139], v[96:99], v[32:35]
	v_mfma_f32_16x16x32_bf16 v[0:3], v[136:139], v[100:103], v[0:3]
	s_setprio 0
	s_waitcnt vmcnt(0)
	v_mov_b64_e32 v[102:103], v[90:91]
	v_mov_b64_e32 v[110:111], v[86:87]
	v_mov_b64_e32 v[98:99], v[82:83]
	v_mov_b64_e32 v[106:107], v[78:79]
	v_mov_b64_e32 v[118:119], v[74:75]
	v_mov_b64_e32 v[122:123], v[70:71]
	v_mov_b64_e32 v[126:127], v[62:63]
	v_mov_b64_e32 v[114:115], v[58:59]
	s_and_b64 vcc, exec, s[4:5]
	v_mov_b64_e32 v[100:101], v[88:89]
	v_mov_b64_e32 v[108:109], v[84:85]
	v_mov_b64_e32 v[96:97], v[80:81]
	v_mov_b64_e32 v[104:105], v[76:77]
	v_mov_b64_e32 v[116:117], v[72:73]
	v_mov_b64_e32 v[120:121], v[68:69]
	v_mov_b64_e32 v[124:125], v[60:61]
	v_mov_b64_e32 v[112:113], v[56:57]
	s_mov_b64 s[4:5], 0
	s_cbranch_vccnz .LBB0_175
; __device__ __forceinline__ void sg_item(CParams& p, int j2, int chunk, int g, bf16_t* smem) {
;     ...
;     const bf16_t* u = (const bf16_t*)(p.ws + WS_U);
;     bf16_t* as = (bf16_t*)(p.ws + WS_AS);
;     const float* bs = p.sgu_b + (size_t)(j2 * 4 + g) * 128;
; #pragma unroll
;     for (int i = 0; i < 2; ++i) {
;         const int pt = wave * 32 + i * 16 + l16;
;         const int row = chunk * 128 + pt;
;         const float bias = bs[pt];
; #pragma unroll
;         for (int j = 0; j < 8; ++j) {
;             const int c = g * 128 + j * 16 + quad * 4;
;             const u32x2 uw = *(const u32x2*)(u + (size_t)row * 512 + c);
;             const float u0 = __uint_as_float(uw.x << 16), u1 = __uint_as_float(uw.x & 0xffff0000u);
;             const float u2 = __uint_as_float(uw.y << 16), u3 = __uint_as_float(uw.y & 0xffff0000u);
;             const f32x4 v = acc[i][j];
;             st4bf(as + frag_off(row, 512 + c, 1024), u0 * (v[0] + bias), u1 * (v[1] + bias), u2 * (v[2] + bias), u3 * (v[3] + bias));
;         }
;     }
	v_and_b32_e32 v69, 15, v128
	v_ashrrev_i32_e32 v56, 1, v129
	s_movk_i32 s2, 0xffe0
	s_lshl_b64 s[4:5], s[78:79], 9
	v_and_or_b32 v56, v56, s2, v69
	s_add_u32 s4, s48, s4
	v_lshl_add_u32 v70, s7, 7, v56
	s_addc_u32 s5, s49, s5
	v_ashrrev_i32_e32 v57, 31, v56
	v_ashrrev_i32_e32 v71, 31, v70
	v_lshl_add_u64 v[62:63], v[56:57], 2, s[4:5]
	v_lshlrev_b64 v[56:57], 10, v[70:71]
	v_lshrrev_b32_e32 v71, 1, v128
	v_and_b32_e32 v58, 24, v71
	v_lshl_add_u64 v[56:57], s[52:53], 0, v[56:57]
	v_lshl_or_b32 v164, s6, 8, v58
	v_lshl_add_u64 v[72:73], v[56:57], 0, v[164:165]
	global_load_dword v132, v[62:63], off
	global_load_dwordx2 v[136:137], v[72:73], off
	global_load_dwordx2 v[140:141], v[72:73], off offset:32
	global_load_dwordx2 v[144:145], v[72:73], off offset:64
	global_load_dwordx2 v[148:149], v[72:73], off offset:96
	global_load_dwordx2 v[152:153], v[72:73], off offset:128
	global_load_dwordx2 v[156:157], v[72:73], off offset:160
	global_load_dwordx2 v[160:161], v[72:73], off offset:192
	global_load_dwordx2 v[172:173], v[72:73], off offset:224
	v_ashrrev_i32_e32 v74, 4, v70
	v_ashrrev_i32_e32 v75, 31, v74
	v_lshlrev_b64 v[74:75], 15, v[74:75]
	s_lshl_b32 s78, s6, 12
	v_lshl_add_u64 v[74:75], s[42:43], 0, v[74:75]
	v_and_or_b32 v58, v71, 16, v69
	v_lshl_add_u64 v[76:77], v[74:75], 0, s[78:79]
	s_mov_b64 s[26:27], 0xe4c4000
	v_mov_b32_e32 v59, v165
	v_lshlrev_b32_e32 v58, 4, v58
	v_lshl_add_u64 v[76:77], v[76:77], 0, s[26:27]
	v_mov_b32_e32 v57, v165
	v_and_b32_e32 v56, 8, v71
	v_lshl_add_u64 v[78:79], v[76:77], 0, v[58:59]
	v_lshl_add_u64 v[78:79], v[78:79], 0, v[56:57]
	s_mov_b32 s4, 0x7ffffffe
	s_mov_b32 s5, s79
	s_mov_b32 s2, 0xe4c4000
	s_mov_b32 s7, s79
	s_or_b32 s6, s78, 0x800
	s_mov_b32 s9, s79
	s_or_b32 s8, s78, 0xc00
	s_mov_b32 s39, s0
	s_waitcnt vmcnt(8)
	v_pk_add_f32 v[80:81], v[92:93], v[132:133] op_sel_hi:[1,0]
	v_pk_add_f32 v[82:83], v[94:95], v[132:133] op_sel_hi:[1,0]
	s_waitcnt vmcnt(7)
	v_lshlrev_b32_e32 v84, 16, v136
	v_and_b32_e32 v85, 0xffff0000, v136
	v_lshlrev_b32_e32 v60, 16, v137
	v_and_b32_e32 v61, 0xffff0000, v137
	v_pk_mul_f32 v[80:81], v[80:81], v[84:85]
	v_pk_mul_f32 v[60:61], v[82:83], v[60:61]
	v_cvt_pk_bf16_f32 v80, v80, v81
	v_cvt_pk_bf16_f32 v81, v60, v61
	global_store_dwordx2 v[78:79], v[80:81], off
	v_and_or_b32 v60, v71, s4, 32
	v_and_or_b32 v60, v60, 48, v69
	v_mov_b32_e32 v61, v165
	v_lshlrev_b32_e32 v60, 4, v60
	v_pk_add_f32 v[64:65], v[64:65], v[132:133] op_sel_hi:[1,0]
	v_pk_add_f32 v[66:67], v[66:67], v[132:133] op_sel_hi:[1,0]
	v_lshl_add_u64 v[76:77], v[76:77], 0, v[60:61]
	v_lshl_add_u64 v[76:77], v[76:77], 0, v[56:57]
	s_or_b32 s4, s78, 0x400
	v_pk_add_f32 v[52:53], v[52:53], v[132:133] op_sel_hi:[1,0]
	v_pk_add_f32 v[54:55], v[54:55], v[132:133] op_sel_hi:[1,0]
	v_pk_add_f32 v[48:49], v[48:49], v[132:133] op_sel_hi:[1,0]
	v_pk_add_f32 v[50:51], v[50:51], v[132:133] op_sel_hi:[1,0]
	v_pk_add_f32 v[44:45], v[44:45], v[132:133] op_sel_hi:[1,0]
	v_pk_add_f32 v[46:47], v[46:47], v[132:133] op_sel_hi:[1,0]
	v_pk_add_f32 v[40:41], v[40:41], v[132:133] op_sel_hi:[1,0]
	v_pk_add_f32 v[42:43], v[42:43], v[132:133] op_sel_hi:[1,0]
	v_pk_add_f32 v[36:37], v[36:37], v[132:133] op_sel_hi:[1,0]
	v_pk_add_f32 v[38:39], v[38:39], v[132:133] op_sel_hi:[1,0]
	v_pk_add_f32 v[32:33], v[32:33], v[132:133] op_sel_hi:[1,0]
	v_pk_add_f32 v[34:35], v[34:35], v[132:133] op_sel_hi:[1,0]
	s_waitcnt vmcnt(6)
	v_lshlrev_b32_e32 v80, 16, v140
	v_and_b32_e32 v81, 0xffff0000, v140
	v_lshlrev_b32_e32 v78, 16, v141
	v_and_b32_e32 v79, 0xffff0000, v141
	v_pk_mul_f32 v[64:65], v[64:65], v[80:81]
	v_pk_mul_f32 v[66:67], v[66:67], v[78:79]
	v_cvt_pk_bf16_f32 v64, v64, v65
	v_cvt_pk_bf16_f32 v65, v66, v67
	global_store_dwordx2 v[76:77], v[64:65], off
	v_lshl_add_u64 v[66:67], v[74:75], 0, s[4:5]
	v_lshl_add_u64 v[76:77], v[66:67], 0, v[58:59]
	v_lshl_add_u64 v[76:77], v[76:77], 0, v[56:57]
	v_add_co_u32_e32 v76, vcc, s2, v76
	s_waitcnt vmcnt(5)
	v_lshlrev_b32_e32 v78, 16, v144
	v_and_b32_e32 v79, 0xffff0000, v144
	v_lshlrev_b32_e32 v64, 16, v145
	v_and_b32_e32 v65, 0xffff0000, v145
	v_pk_mul_f32 v[52:53], v[52:53], v[78:79]
	v_pk_mul_f32 v[54:55], v[54:55], v[64:65]
	v_addc_co_u32_e32 v77, vcc, 0, v77, vcc
	v_cvt_pk_bf16_f32 v52, v52, v53
	v_cvt_pk_bf16_f32 v53, v54, v55
	global_store_dwordx2 v[76:77], v[52:53], off
	v_lshl_add_u64 v[54:55], v[66:67], 0, v[60:61]
	v_lshl_add_u64 v[54:55], v[54:55], 0, v[56:57]
	v_add_co_u32_e32 v54, vcc, s2, v54
	s_waitcnt vmcnt(4)
	v_lshlrev_b32_e32 v64, 16, v148
	v_and_b32_e32 v65, 0xffff0000, v148
	v_lshlrev_b32_e32 v52, 16, v149
	v_and_b32_e32 v53, 0xffff0000, v149
	v_pk_mul_f32 v[48:49], v[48:49], v[64:65]
	v_pk_mul_f32 v[50:51], v[50:51], v[52:53]
	v_addc_co_u32_e32 v55, vcc, 0, v55, vcc
	v_cvt_pk_bf16_f32 v48, v48, v49
	v_cvt_pk_bf16_f32 v49, v50, v51
	global_store_dwordx2 v[54:55], v[48:49], off
	v_lshl_add_u64 v[50:51], v[74:75], 0, s[6:7]
	v_lshl_add_u64 v[52:53], v[50:51], 0, v[58:59]
	v_lshl_add_u64 v[52:53], v[52:53], 0, v[56:57]
	v_add_co_u32_e32 v52, vcc, s2, v52
	s_waitcnt vmcnt(3)
	v_lshlrev_b32_e32 v54, 16, v152
	v_and_b32_e32 v55, 0xffff0000, v152
	v_lshlrev_b32_e32 v48, 16, v153
	v_and_b32_e32 v49, 0xffff0000, v153
	v_pk_mul_f32 v[44:45], v[44:45], v[54:55]
	v_pk_mul_f32 v[46:47], v[46:47], v[48:49]
	v_addc_co_u32_e32 v53, vcc, 0, v53, vcc
	v_cvt_pk_bf16_f32 v44, v44, v45
	v_cvt_pk_bf16_f32 v45, v46, v47
	global_store_dwordx2 v[52:53], v[44:45], off
	v_lshl_add_u64 v[46:47], v[50:51], 0, v[60:61]
	v_lshl_add_u64 v[46:47], v[46:47], 0, v[56:57]
	v_add_co_u32_e32 v46, vcc, s2, v46
	s_waitcnt vmcnt(2)
; __device__ __forceinline__ void sg_item(CParams& p, int j2, int chunk, int g, bf16_t* smem) {
;     ...
; #pragma unroll
;     for (int i = 0; i < 2; ++i) {
;         const int pt = wave * 32 + i * 16 + l16;
;         const int row = chunk * 128 + pt;
;         const float bias = bs[pt];
; #pragma unroll
;         for (int j = 0; j < 8; ++j) {
;             const int c = g * 128 + j * 16 + quad * 4;
;             const u32x2 uw = *(const u32x2*)(u + (size_t)row * 512 + c);
;             const float u0 = __uint_as_float(uw.x << 16), u1 = __uint_as_float(uw.x & 0xffff0000u);
;             const float u2 = __uint_as_float(uw.y << 16), u3 = __uint_as_float(uw.y & 0xffff0000u);
;             const f32x4 v = acc[i][j];
;             st4bf(as + frag_off(row, 512 + c, 1024), u0 * (v[0] + bias), u1 * (v[1] + bias), u2 * (v[2] + bias), u3 * (v[3] + bias));
;         }
;     }
	v_lshlrev_b32_e32 v48, 16, v156
	v_and_b32_e32 v49, 0xffff0000, v156
	v_lshlrev_b32_e32 v44, 16, v157
	v_and_b32_e32 v45, 0xffff0000, v157
	v_pk_mul_f32 v[40:41], v[40:41], v[48:49]
	v_pk_mul_f32 v[42:43], v[42:43], v[44:45]
	v_addc_co_u32_e32 v47, vcc, 0, v47, vcc
	v_cvt_pk_bf16_f32 v40, v40, v41
	v_cvt_pk_bf16_f32 v41, v42, v43
	global_store_dwordx2 v[46:47], v[40:41], off
	v_lshl_add_u64 v[42:43], v[74:75], 0, s[8:9]
	v_lshl_add_u64 v[44:45], v[42:43], 0, v[58:59]
	v_lshl_add_u64 v[44:45], v[44:45], 0, v[56:57]
	v_add_co_u32_e32 v44, vcc, s2, v44
	v_lshl_add_u64 v[42:43], v[42:43], 0, v[60:61]
	s_nop 0
	v_addc_co_u32_e32 v45, vcc, 0, v45, vcc
	v_lshl_add_u64 v[42:43], v[42:43], 0, v[56:57]
	v_add_co_u32_e32 v42, vcc, s2, v42
	s_waitcnt vmcnt(1)
	v_lshlrev_b32_e32 v46, 16, v160
	v_and_b32_e32 v47, 0xffff0000, v160
	v_lshlrev_b32_e32 v40, 16, v161
	v_and_b32_e32 v41, 0xffff0000, v161
	v_pk_mul_f32 v[36:37], v[36:37], v[46:47]
	v_pk_mul_f32 v[38:39], v[38:39], v[40:41]
	v_cvt_pk_bf16_f32 v36, v36, v37
	v_cvt_pk_bf16_f32 v37, v38, v39
	global_store_dwordx2 v[44:45], v[36:37], off
	v_or_b32_e32 v40, 16, v70
	v_ashrrev_i32_e32 v41, 31, v40
	v_lshlrev_b64 v[36:37], 10, v[40:41]
	v_lshl_add_u64 v[36:37], s[52:53], 0, v[36:37]
	v_addc_co_u32_e32 v43, vcc, 0, v43, vcc
	v_lshl_add_u64 v[36:37], v[36:37], 0, v[164:165]
	s_waitcnt vmcnt(0)
	v_lshlrev_b32_e32 v44, 16, v172
	v_and_b32_e32 v45, 0xffff0000, v172
	v_lshlrev_b32_e32 v38, 16, v173
	v_and_b32_e32 v39, 0xffff0000, v173
	v_pk_mul_f32 v[32:33], v[32:33], v[44:45]
	v_pk_mul_f32 v[34:35], v[34:35], v[38:39]
	v_cvt_pk_bf16_f32 v32, v32, v33
	v_cvt_pk_bf16_f32 v33, v34, v35
	global_store_dwordx2 v[42:43], v[32:33], off
	global_load_dwordx2 v[48:49], v[36:37], off
	global_load_dword v52, v[62:63], off offset:64
	global_load_dwordx2 v[64:65], v[36:37], off offset:32
	global_load_dwordx2 v[68:69], v[36:37], off offset:64
	global_load_dwordx2 v[72:73], v[36:37], off offset:96
	global_load_dwordx2 v[76:77], v[36:37], off offset:128
	global_load_dwordx2 v[80:81], v[36:37], off offset:160
	global_load_dwordx2 v[84:85], v[36:37], off offset:192
	global_load_dwordx2 v[88:89], v[36:37], off offset:224
	s_nop 0
	v_ashrrev_i32_e32 v38, 4, v40
	v_ashrrev_i32_e32 v39, 31, v38
	v_lshlrev_b64 v[38:39], 15, v[38:39]
	v_lshl_add_u64 v[38:39], s[42:43], 0, v[38:39]
	v_lshl_add_u64 v[40:41], v[38:39], 0, s[78:79]
	v_lshl_add_u64 v[40:41], v[40:41], 0, s[26:27]
	v_lshl_add_u64 v[42:43], v[40:41], 0, v[58:59]
	v_lshl_add_u64 v[42:43], v[42:43], 0, v[56:57]
	s_waitcnt vmcnt(8)
	v_lshlrev_b32_e32 v44, 16, v48
	v_and_b32_e32 v45, 0xffff0000, v48
	s_waitcnt vmcnt(7)
	v_pk_add_f32 v[28:29], v[28:29], v[52:53] op_sel_hi:[1,0]
	v_lshlrev_b32_e32 v34, 16, v49
	v_and_b32_e32 v35, 0xffff0000, v49
	v_pk_add_f32 v[30:31], v[30:31], v[52:53] op_sel_hi:[1,0]
	v_pk_mul_f32 v[28:29], v[28:29], v[44:45]
	v_pk_mul_f32 v[30:31], v[30:31], v[34:35]
	v_cvt_pk_bf16_f32 v28, v28, v29
	v_cvt_pk_bf16_f32 v29, v30, v31
	global_store_dwordx2 v[42:43], v[28:29], off
	v_pk_add_f32 v[24:25], v[24:25], v[52:53] op_sel_hi:[1,0]
	v_pk_add_f32 v[26:27], v[26:27], v[52:53] op_sel_hi:[1,0]
	v_lshl_add_u64 v[30:31], v[40:41], 0, v[60:61]
	v_lshl_add_u64 v[30:31], v[30:31], 0, v[56:57]
	v_pk_add_f32 v[20:21], v[20:21], v[52:53] op_sel_hi:[1,0]
	v_pk_add_f32 v[22:23], v[22:23], v[52:53] op_sel_hi:[1,0]
	v_pk_add_f32 v[16:17], v[16:17], v[52:53] op_sel_hi:[1,0]
	v_pk_add_f32 v[18:19], v[18:19], v[52:53] op_sel_hi:[1,0]
	v_pk_add_f32 v[12:13], v[12:13], v[52:53] op_sel_hi:[1,0]
	v_pk_add_f32 v[14:15], v[14:15], v[52:53] op_sel_hi:[1,0]
	v_pk_add_f32 v[8:9], v[8:9], v[52:53] op_sel_hi:[1,0]
	v_pk_add_f32 v[10:11], v[10:11], v[52:53] op_sel_hi:[1,0]
	v_pk_add_f32 v[4:5], v[4:5], v[52:53] op_sel_hi:[1,0]
	v_pk_add_f32 v[6:7], v[6:7], v[52:53] op_sel_hi:[1,0]
	v_pk_add_f32 v[0:1], v[0:1], v[52:53] op_sel_hi:[1,0]
	v_pk_add_f32 v[2:3], v[2:3], v[52:53] op_sel_hi:[1,0]
	s_waitcnt vmcnt(6)
; __device__ __forceinline__ void sg_item(CParams& p, int j2, int chunk, int g, bf16_t* smem) {
;     ...
; #pragma unroll
;     for (int i = 0; i < 2; ++i) {
;         const int pt = wave * 32 + i * 16 + l16;
;         const int row = chunk * 128 + pt;
;         const float bias = bs[pt];
; #pragma unroll
;         for (int j = 0; j < 8; ++j) {
;             const int c = g * 128 + j * 16 + quad * 4;
;             const u32x2 uw = *(const u32x2*)(u + (size_t)row * 512 + c);
;             const float u0 = __uint_as_float(uw.x << 16), u1 = __uint_as_float(uw.x & 0xffff0000u);
;             const float u2 = __uint_as_float(uw.y << 16), u3 = __uint_as_float(uw.y & 0xffff0000u);
;             const f32x4 v = acc[i][j];
;             st4bf(as + frag_off(row, 512 + c, 1024), u0 * (v[0] + bias), u1 * (v[1] + bias), u2 * (v[2] + bias), u3 * (v[3] + bias));
;         }
;     }
	v_lshlrev_b32_e32 v34, 16, v64
	v_and_b32_e32 v35, 0xffff0000, v64
	v_lshlrev_b32_e32 v28, 16, v65
	v_and_b32_e32 v29, 0xffff0000, v65
	v_pk_mul_f32 v[24:25], v[24:25], v[34:35]
	v_pk_mul_f32 v[26:27], v[26:27], v[28:29]
	v_cvt_pk_bf16_f32 v24, v24, v25
	v_cvt_pk_bf16_f32 v25, v26, v27
	global_store_dwordx2 v[30:31], v[24:25], off
	v_lshl_add_u64 v[26:27], v[38:39], 0, s[4:5]
	v_lshl_add_u64 v[28:29], v[26:27], 0, v[58:59]
	v_lshl_add_u64 v[28:29], v[28:29], 0, v[56:57]
	v_add_co_u32_e32 v28, vcc, s2, v28
	s_waitcnt vmcnt(5)
	v_lshlrev_b32_e32 v30, 16, v68
	v_and_b32_e32 v31, 0xffff0000, v68
	v_lshlrev_b32_e32 v24, 16, v69
	v_and_b32_e32 v25, 0xffff0000, v69
	v_pk_mul_f32 v[20:21], v[20:21], v[30:31]
	v_pk_mul_f32 v[22:23], v[22:23], v[24:25]
	v_addc_co_u32_e32 v29, vcc, 0, v29, vcc
	v_cvt_pk_bf16_f32 v20, v20, v21
	v_cvt_pk_bf16_f32 v21, v22, v23
	global_store_dwordx2 v[28:29], v[20:21], off
	v_lshl_add_u64 v[22:23], v[26:27], 0, v[60:61]
	v_lshl_add_u64 v[22:23], v[22:23], 0, v[56:57]
	v_add_co_u32_e32 v22, vcc, s2, v22
	s_waitcnt vmcnt(4)
	v_lshlrev_b32_e32 v24, 16, v72
	v_and_b32_e32 v25, 0xffff0000, v72
	v_lshlrev_b32_e32 v20, 16, v73
	v_and_b32_e32 v21, 0xffff0000, v73
	v_pk_mul_f32 v[16:17], v[16:17], v[24:25]
	v_pk_mul_f32 v[18:19], v[18:19], v[20:21]
	v_addc_co_u32_e32 v23, vcc, 0, v23, vcc
	v_cvt_pk_bf16_f32 v16, v16, v17
	v_cvt_pk_bf16_f32 v17, v18, v19
	global_store_dwordx2 v[22:23], v[16:17], off
	v_lshl_add_u64 v[18:19], v[38:39], 0, s[6:7]
	v_lshl_add_u64 v[20:21], v[18:19], 0, v[58:59]
	v_lshl_add_u64 v[20:21], v[20:21], 0, v[56:57]
	v_add_co_u32_e32 v20, vcc, s2, v20
	s_waitcnt vmcnt(3)
	v_lshlrev_b32_e32 v22, 16, v76
	v_and_b32_e32 v23, 0xffff0000, v76
	v_lshlrev_b32_e32 v16, 16, v77
	v_and_b32_e32 v17, 0xffff0000, v77
	v_pk_mul_f32 v[12:13], v[12:13], v[22:23]
	v_pk_mul_f32 v[14:15], v[14:15], v[16:17]
	v_addc_co_u32_e32 v21, vcc, 0, v21, vcc
	v_cvt_pk_bf16_f32 v12, v12, v13
	v_cvt_pk_bf16_f32 v13, v14, v15
	global_store_dwordx2 v[20:21], v[12:13], off
	v_lshl_add_u64 v[14:15], v[18:19], 0, v[60:61]
	v_lshl_add_u64 v[14:15], v[14:15], 0, v[56:57]
	v_add_co_u32_e32 v14, vcc, s2, v14
	s_waitcnt vmcnt(2)
	v_lshlrev_b32_e32 v16, 16, v80
	v_and_b32_e32 v17, 0xffff0000, v80
	v_lshlrev_b32_e32 v12, 16, v81
	v_and_b32_e32 v13, 0xffff0000, v81
	v_pk_mul_f32 v[8:9], v[8:9], v[16:17]
	v_pk_mul_f32 v[10:11], v[10:11], v[12:13]
	v_addc_co_u32_e32 v15, vcc, 0, v15, vcc
	v_cvt_pk_bf16_f32 v8, v8, v9
	v_cvt_pk_bf16_f32 v9, v10, v11
	global_store_dwordx2 v[14:15], v[8:9], off
	v_lshl_add_u64 v[10:11], v[38:39], 0, s[8:9]
	v_lshl_add_u64 v[12:13], v[10:11], 0, v[58:59]
	v_lshl_add_u64 v[12:13], v[12:13], 0, v[56:57]
	v_add_co_u32_e32 v12, vcc, s2, v12
	s_waitcnt vmcnt(1)
	v_lshlrev_b32_e32 v14, 16, v84
	v_and_b32_e32 v15, 0xffff0000, v84
	v_lshlrev_b32_e32 v8, 16, v85
	v_and_b32_e32 v9, 0xffff0000, v85
	v_pk_mul_f32 v[4:5], v[4:5], v[14:15]
	v_pk_mul_f32 v[6:7], v[6:7], v[8:9]
	v_addc_co_u32_e32 v13, vcc, 0, v13, vcc
	v_cvt_pk_bf16_f32 v4, v4, v5
	v_cvt_pk_bf16_f32 v5, v6, v7
	global_store_dwordx2 v[12:13], v[4:5], off
	v_lshl_add_u64 v[6:7], v[10:11], 0, v[60:61]
	v_lshl_add_u64 v[6:7], v[6:7], 0, v[56:57]
	v_add_co_u32_e32 v6, vcc, 0xe4c4000, v6
	s_waitcnt vmcnt(0)
	v_lshlrev_b32_e32 v8, 16, v88
	v_and_b32_e32 v9, 0xffff0000, v88
	v_lshlrev_b32_e32 v4, 16, v89
	v_and_b32_e32 v5, 0xffff0000, v89
	v_pk_mul_f32 v[0:1], v[0:1], v[8:9]
	v_pk_mul_f32 v[2:3], v[2:3], v[4:5]
	v_cvt_pk_bf16_f32 v0, v0, v1
	v_cvt_pk_bf16_f32 v1, v2, v3
	v_addc_co_u32_e32 v7, vcc, 0, v7, vcc
	global_store_dwordx2 v[6:7], v[0:1], off
